# S.next tile decode: divide by group size takes a guarded shift when gsz==8 (generic divide kept as slow path), all 4 GEMMs
# baseline (speedup 1.0000x reference)
;     __host__ __device__ bool next(int i, Unit& u) const {
;         const long L = (long)i * G + c; if (L >= nwg) return false;
;         int wgid = (int)L; { const int q = nwg / NXCD, r = nwg % NXCD, xcd = wgid % NXCD, off = wgid / NXCD; wgid = (xcd < r ? xcd * (q + 1) : r * (q + 1) + (xcd - r) * q) + off; }
;         const int nig = WGM * nN, gid = wgid / nig, fm = gid * WGM, gsz = (nM - fm) < WGM ? (nM - fm) : WGM;
;         u.pm = fm + ((wgid % nig) % gsz); u.pn = (wgid % nig) / gsz; return true;
.LBB0_216:
	s_add_i32 s67, s1, 1
	s_mul_i32 s38, s67, s29
	s_mul_hi_u32 s39, s67, s28
	s_add_i32 s39, s39, s38
	s_mul_i32 s38, s67, s28
	s_add_u32 s38, s38, s2
	s_addc_u32 s39, s39, s3
	s_waitcnt lgkmcnt(0)
	v_mov_b64_e32 v[0:1], s[16:17]
	v_cmp_ge_i64_e32 vcc, s[38:39], v[0:1]
	v_cmp_lt_i64_e64 s[44:45], s[38:39], v[0:1]
	s_cbranch_vccnz .LBB0_218
	s_ashr_i32 s39, s38, 31
	s_lshr_b32 s39, s39, 29
	s_add_i32 s39, s38, s39
	s_ashr_i32 s50, s39, 3
	s_and_b32 s39, s39, -8
	s_sub_i32 s38, s38, s39
	s_lshr_b32 s39, s38, 31
	s_or_b32 s39, s95, s39
	s_mul_i32 s38, s39, s38
	s_add_i32 s38, s38, s50
	s_abs_i32 s50, s38
	v_readlane_b32 s51, v255, 15
	s_mul_hi_u32 s51, s50, s51
	s_mul_i32 s52, s51, s94
	s_sub_i32 s50, s50, s52
	s_ashr_i32 s39, s38, 31
	s_add_i32 s52, s51, 1
	s_sub_i32 s53, s50, s94
	s_cmp_ge_u32 s50, s94
	s_cselect_b32 s51, s52, s51
	s_cselect_b32 s50, s53, s50
	s_add_i32 s52, s51, 1
	s_cmp_ge_u32 s50, s94
	s_cselect_b32 s50, s52, s51
	s_xor_b32 s50, s50, s39
	s_sub_i32 s39, s50, s39
	s_lshl_b32 s50, s39, 3
	s_sub_i32 s51, 0x80, s50
	s_min_i32 s51, s51, 8
	s_mul_i32 s39, s39, s94
	s_sub_i32 s38, s38, s39
	s_cmp_eq_u32 s51, 8
	s_cbranch_scc0 .Ldiv1_slow
	s_cmp_lt_i32 s38, 0
	s_cbranch_scc1 .Ldiv1_slow
	s_lshr_b32 s70, s38, 3
	s_branch .Ldiv1_done
.Ldiv1_slow:
	s_abs_i32 s52, s51
	v_cvt_f32_u32_e32 v0, s52
	s_sub_i32 s56, 0, s52
	v_rcp_iflag_f32_e32 v0, v0
	s_abs_i32 s53, s38
	s_xor_b32 s39, s38, s51
	s_ashr_i32 s39, s39, 31
	v_mul_f32_e32 v0, 0x4f7ffffe, v0
	v_cvt_u32_f32_e32 v0, v0
	s_nop 0
	v_readfirstlane_b32 s57, v0
	s_mul_i32 s56, s56, s57
	s_mul_hi_u32 s56, s57, s56
	s_add_i32 s57, s57, s56
	s_mul_hi_u32 s56, s53, s57
	s_mul_i32 s57, s56, s52
	s_sub_i32 s53, s53, s57
	s_add_i32 s57, s56, 1
	s_sub_i32 s70, s53, s52
	s_cmp_ge_u32 s53, s52
	s_cselect_b32 s56, s57, s56
	s_cselect_b32 s53, s70, s53
	s_add_i32 s57, s56, 1
	s_cmp_ge_u32 s53, s52
	s_cselect_b32 s52, s57, s56
	s_xor_b32 s52, s52, s39
	s_sub_i32 s70, s52, s39
.Ldiv1_done:
	s_mul_i32 s39, s70, s51
	s_sub_i32 s38, s38, s39
	s_add_i32 s72, s38, s50

;     __host__ __device__ bool next(int i, Unit& u) const {
;     ...
;         int wgid = (int)L; { const int q = nwg / NXCD, r = nwg % NXCD, xcd = wgid % NXCD, off = wgid / NXCD; wgid = (xcd < r ? xcd * (q + 1) : r * (q + 1) + (xcd - r) * q) + off; }
;         const int nig = WGM * nN, gid = wgid / nig, fm = gid * WGM, gsz = (nM - fm) < WGM ? (nM - fm) : WGM;
;         u.pm = fm + ((wgid % nig) % gsz); u.pn = (wgid % nig) / gsz; return true;
.LBB0_1635:
	s_ashr_i32 s42, s51, 3
	s_add_i32 s42, s63, s42
	s_ashr_i32 s43, s42, 31
	s_lshr_b32 s43, s43, 27
	s_add_i32 s43, s42, s43
	s_ashr_i32 s51, s43, 5
	s_lshl_b32 s62, s51, 3
	s_sub_i32 s51, 0x80, s62
	s_min_i32 s63, s51, 8
	s_andn2_b32 s43, s43, 31
	s_sub_i32 s42, s42, s43
	s_cmp_eq_u32 s63, 8
	s_cbranch_scc0 .Ldiv2_slow
	s_cmp_lt_i32 s42, 0
	s_cbranch_scc1 .Ldiv2_slow
	s_lshr_b32 s51, s42, 3
	s_branch .Ldiv2_done
.Ldiv2_slow:
	s_abs_i32 s51, s63
	v_cvt_f32_u32_e32 v0, s51
	s_sub_i32 s65, 0, s51
	v_rcp_iflag_f32_e32 v0, v0
	s_abs_i32 s43, s42
	s_xor_b32 s64, s42, s63
	s_ashr_i32 s64, s64, 31
	v_mul_f32_e32 v0, 0x4f7ffffe, v0
	v_cvt_u32_f32_e32 v0, v0
	s_nop 0
	v_readfirstlane_b32 s76, v0
	s_mul_i32 s65, s65, s76
	s_mul_hi_u32 s65, s76, s65
	s_add_i32 s76, s76, s65
	s_mul_hi_u32 s65, s43, s76
	s_mul_i32 s76, s65, s51
	s_sub_i32 s43, s43, s76
	s_add_i32 s78, s65, 1
	s_sub_i32 s76, s43, s51
	s_cmp_ge_u32 s43, s51
	s_cselect_b32 s65, s78, s65
	s_cselect_b32 s43, s76, s43
	s_add_i32 s76, s65, 1
	s_cmp_ge_u32 s43, s51
	s_cselect_b32 s43, s76, s65
	s_xor_b32 s43, s43, s64
	s_sub_i32 s51, s43, s64
.Ldiv2_done:
	s_mul_i32 s43, s51, s63
	s_sub_i32 s42, s42, s43
	s_add_i32 s76, s62, s42

;     __host__ __device__ bool next(int i, Unit& u) const {
;     ...
;         int wgid = (int)L; { const int q = nwg / NXCD, r = nwg % NXCD, xcd = wgid % NXCD, off = wgid / NXCD; wgid = (xcd < r ? xcd * (q + 1) : r * (q + 1) + (xcd - r) * q) + off; }
;         const int nig = WGM * nN, gid = wgid / nig, fm = gid * WGM, gsz = (nM - fm) < WGM ? (nM - fm) : WGM;
;         u.pm = fm + ((wgid % nig) % gsz); u.pn = (wgid % nig) / gsz; return true;
.LBB0_1750:
	s_ashr_i32 s48, s50, 3
	s_add_i32 s48, s52, s48
	s_ashr_i32 s49, s48, 31
	s_lshr_b32 s49, s49, 25
	s_add_i32 s49, s48, s49
	s_ashr_i32 s50, s49, 7
	s_lshl_b32 s50, s50, 3
	s_sub_i32 s51, 0x80, s50
	s_min_i32 s51, s51, 8
	s_and_b32 s49, s49, 0xffffff80
	s_sub_i32 s49, s48, s49
	s_cmp_eq_u32 s51, 8
	s_cbranch_scc0 .Ldiv3_slow
	s_cmp_lt_i32 s49, 0
	s_cbranch_scc1 .Ldiv3_slow
	s_lshr_b32 s48, s49, 3
	s_branch .Ldiv3_done
.Ldiv3_slow:
	s_abs_i32 s52, s51
	v_cvt_f32_u32_e32 v0, s52
	s_sub_i32 s54, 0, s52
	v_rcp_iflag_f32_e32 v0, v0
	s_abs_i32 s48, s49
	s_xor_b32 s53, s49, s51
	s_ashr_i32 s53, s53, 31
	v_mul_f32_e32 v0, 0x4f7ffffe, v0
	v_cvt_u32_f32_e32 v0, v0
	s_nop 0
	v_readfirstlane_b32 s55, v0
	s_mul_i32 s54, s54, s55
	s_mul_hi_u32 s54, s55, s54
	s_add_i32 s55, s55, s54
	s_mul_hi_u32 s54, s48, s55
	s_mul_i32 s55, s54, s52
	s_sub_i32 s48, s48, s55
	s_add_i32 s56, s54, 1
	s_sub_i32 s55, s48, s52
	s_cmp_ge_u32 s48, s52
	s_cselect_b32 s54, s56, s54
	s_cselect_b32 s48, s55, s48
	s_add_i32 s55, s54, 1
	s_cmp_ge_u32 s48, s52
	s_cselect_b32 s48, s55, s54
	s_xor_b32 s48, s48, s53
	s_sub_i32 s48, s48, s53
.Ldiv3_done:
	s_mul_i32 s51, s48, s51
	s_sub_i32 s49, s49, s51
	s_add_i32 s50, s50, s49

;     __host__ __device__ bool next(int i, Unit& u) const {
;     ...
;         int wgid = (int)L; { const int q = nwg / NXCD, r = nwg % NXCD, xcd = wgid % NXCD, off = wgid / NXCD; wgid = (xcd < r ? xcd * (q + 1) : r * (q + 1) + (xcd - r) * q) + off; }
;         const int nig = WGM * nN, gid = wgid / nig, fm = gid * WGM, gsz = (nM - fm) < WGM ? (nM - fm) : WGM;
;         u.pm = fm + ((wgid % nig) % gsz); u.pn = (wgid % nig) / gsz; return true;
.LBB0_1843:
	s_ashr_i32 s46, s48, 3
	s_add_i32 s46, s50, s46
	s_ashr_i32 s47, s46, 31
	s_lshr_b32 s47, s47, 27
	s_add_i32 s47, s46, s47
	s_ashr_i32 s48, s47, 5
	s_lshl_b32 s48, s48, 3
	s_sub_i32 s49, 0x80, s48
	s_min_i32 s49, s49, 8
	s_andn2_b32 s47, s47, 31
	s_sub_i32 s47, s46, s47
	s_cmp_eq_u32 s49, 8
	s_cbranch_scc0 .Ldiv4_slow
	s_cmp_lt_i32 s47, 0
	s_cbranch_scc1 .Ldiv4_slow
	s_lshr_b32 s46, s47, 3
	s_branch .Ldiv4_done
.Ldiv4_slow:
	s_abs_i32 s50, s49
	v_cvt_f32_u32_e32 v0, s50
	s_sub_i32 s52, 0, s50
	v_rcp_iflag_f32_e32 v0, v0
	s_abs_i32 s46, s47
	s_xor_b32 s51, s47, s49
	s_ashr_i32 s51, s51, 31
	v_mul_f32_e32 v0, 0x4f7ffffe, v0
	v_cvt_u32_f32_e32 v0, v0
	s_nop 0
	v_readfirstlane_b32 s53, v0
	s_mul_i32 s52, s52, s53
	s_mul_hi_u32 s52, s53, s52
	s_add_i32 s53, s53, s52
	s_mul_hi_u32 s52, s46, s53
	s_mul_i32 s53, s52, s50
	s_sub_i32 s46, s46, s53
	s_add_i32 s56, s52, 1
	s_sub_i32 s53, s46, s50
	s_cmp_ge_u32 s46, s50
	s_cselect_b32 s52, s56, s52
	s_cselect_b32 s46, s53, s46
	s_add_i32 s53, s52, 1
	s_cmp_ge_u32 s46, s50
	s_cselect_b32 s46, s53, s52
	s_xor_b32 s46, s46, s51
	s_sub_i32 s46, s46, s51
.Ldiv4_done:
	s_mul_i32 s49, s46, s49
	s_sub_i32 s47, s47, s49
	s_add_i32 s48, s48, s47
